# loop-edge rotation (7.11): in-proj K-loop head SALU and DMA-address setup moved in front of the loop-back barrier
# baseline (speedup 1.0000x reference)
; #define PG8_STAGE(bufoff, gbase, voff) do { _Pragma("unroll") for (int _i = 0; _i < 2; ++_i) \
;         __builtin_amdgcn_global_load_lds((const unsigned*)((const char*)(gbase) + (voff)[_i]), (LAS unsigned*)(lds + (bufoff) + ldsw + _i * 8192), 16, 0, 0); } while (0)
; #define PG8_LDA(dst, b, h) do { _Pragma("unroll") for (int m = 0; m < 4; ++m) _Pragma("unroll") for (int k = 0; k < 2; ++k) dst[m][k] = *(const LAS bf16x8*)(lds + PG8_SA(b, h) + aoff + m * 2048 + k * 1024); } while (0)
; #define PG8_LDB(dst, b, h) do { _Pragma("unroll") for (int n = 0; n < 2; ++n) _Pragma("unroll") for (int k = 0; k < 2; ++k) dst[n][k] = *(const LAS bf16x8*)(lds + PG8_SB(b, h) + boff + n * 2048 + k * 1024); } while (0)
; #define PG8_MMA(ai, bj, At, Bt) do { __builtin_amdgcn_s_setprio(1); _Pragma("unroll") for (int m = 0; m < 4; ++m) _Pragma("unroll") for (int n = 0; n < 2; ++n) _Pragma("unroll") for (int k = 0; k < 2; ++k) \
;         acc[ai][bj][m][n] = __builtin_amdgcn_mfma_f32_16x16x32_bf16(Bt[n][k], At[m][k], acc[ai][bj][m][n], 0, 0, 0); __builtin_amdgcn_s_setprio(0); } while (0)
; #define PG8_WAIT_V(n) asm volatile("s_waitcnt vmcnt(" #n ")" ::: "memory")
; #define PG8_WAIT_L(n) asm volatile("s_waitcnt lgkmcnt(" #n ")" ::: "memory")
; template <class Epi, class Sched>
; __device__ __forceinline__ void gemm_phase(const int TID, LAS unsigned char* lds, const int lda, const int ldb, const Sched& S, const Epi& E) {
;     ...
;         for (int t = 0; t < nt; t += 2) {
;             const bool last = (t == nt - 2);
;             const char* a1 = cA + (size_t)(t + 1) * kstep;
;             const char* a2 = last ? nA : cA + (size_t)(t + 2) * kstep; const char* b2 = last ? nB : cB + (size_t)(t + 2) * kstep;
;             const char* a3 = a2 + kstep; const char* b3 = b2 + kstep;
;             PG8_LDB(B0, 0, 0); PG8_SCHED; PG8_LDA(At, 0, 0); PG8_STAGE(PG8_SA(1, 1), a1 + hA, voffA);
;             PG8_WAIT_L(8); PG8_BAR; PG8_WAIT_L(0); PG8_MMA(0, 0, At, B0); PG8_BAR; PG8_SCHED;
;             PG8_LDB(B1, 0, 1); PG8_STAGE(PG8_SB(0, 0), b2, voffB);
;             PG8_BAR; PG8_WAIT_L(0); PG8_MMA(0, 1, At, B1); PG8_BAR;
;             PG8_LDA(At, 0, 1); PG8_STAGE(PG8_SA(0, 0), a2, voffA);
;             PG8_BAR; PG8_WAIT_L(0); PG8_MMA(1, 0, At, B0); PG8_BAR; PG8_SCHED;
;             PG8_STAGE(PG8_SB(0, 1), b2 + hB, voffB);
;             PG8_WAIT_V(6); PG8_BAR; PG8_MMA(1, 1, At, B1); PG8_BAR;
.Lk1_noprio:
	v_add_u32_e32 v154, 0x10000, v13
	ds_read_b128 v[150:153], v154
	ds_read_b128 v[158:161], v154 offset:1024
	ds_read_b128 v[162:165], v154 offset:2048
	ds_read_b128 v[166:169], v154 offset:3072
	s_add_u32 s8, s46, 0xfff80080
	s_addc_u32 s9, s47, -1
	s_add_i32 s10, 0, 0x10000
	s_cmp_eq_u32 s29, 28
	s_cselect_b32 s51, s43, s9
	s_cselect_b32 s50, s42, s8
	s_cselect_b32 s49, s45, s24
	s_cselect_b32 s48, s44, s3
	v_lshl_add_u64 v[154:155], s[46:47], 0, v[148:149]
	s_add_i32 m0, s57, 0xc000
.Lk1_body:
	ds_read_b128 v[170:173], v157
	ds_read_b128 v[174:177], v157 offset:1024
	ds_read_b128 v[178:181], v157 offset:2048
	ds_read_b128 v[196:199], v157 offset:3072
	ds_read_b128 v[200:203], v157 offset:4096
	ds_read_b128 v[204:207], v157 offset:5120
	ds_read_b128 v[208:211], v157 offset:6144
	ds_read_b128 v[212:215], v157 offset:7168
	global_load_lds_dwordx4 v[154:155], off
	v_lshl_add_u64 v[154:155], s[46:47], 0, v[146:147]
	s_add_i32 m0, s57, 0xe000
	s_nop 0
	global_load_lds_dwordx4 v[154:155], off
	s_waitcnt lgkmcnt(8)
	s_barrier
	s_waitcnt lgkmcnt(0)
	s_waitcnt lgkmcnt(0)
	v_mfma_f32_16x16x32_bf16 v[130:133], v[150:153], v[170:173], v[130:133]
	v_mfma_f32_16x16x32_bf16 v[126:129], v[162:165], v[170:173], v[126:129]
	v_mfma_f32_16x16x32_bf16 v[114:117], v[150:153], v[178:181], v[114:117]
	v_mfma_f32_16x16x32_bf16 v[110:113], v[162:165], v[178:181], v[110:113]
	v_mfma_f32_16x16x32_bf16 v[98:101], v[150:153], v[200:203], v[98:101]
	v_mfma_f32_16x16x32_bf16 v[94:97], v[162:165], v[200:203], v[94:97]
	v_mfma_f32_16x16x32_bf16 v[82:85], v[150:153], v[208:211], v[82:85]
	v_mfma_f32_16x16x32_bf16 v[78:81], v[162:165], v[208:211], v[78:81]
	v_mfma_f32_16x16x32_bf16 v[130:133], v[158:161], v[174:177], v[130:133]
	v_mfma_f32_16x16x32_bf16 v[126:129], v[166:169], v[174:177], v[126:129]
	v_mfma_f32_16x16x32_bf16 v[114:117], v[158:161], v[196:199], v[114:117]
	v_mfma_f32_16x16x32_bf16 v[110:113], v[166:169], v[196:199], v[110:113]
	v_mfma_f32_16x16x32_bf16 v[98:101], v[158:161], v[204:207], v[98:101]
	v_mfma_f32_16x16x32_bf16 v[94:97], v[166:169], v[204:207], v[94:97]
	v_mfma_f32_16x16x32_bf16 v[82:85], v[158:161], v[212:215], v[82:85]
	v_mfma_f32_16x16x32_bf16 v[78:81], v[166:169], v[212:215], v[78:81]
	s_barrier
	s_add_i32 s8, 0, 0x14000
	v_add_u32_e32 v154, s8, v13
	s_add_i32 s9, s10, s56
	ds_read_b128 v[216:219], v154
	ds_read_b128 v[220:223], v154 offset:1024
	ds_read_b128 v[236:239], v154 offset:2048
	ds_read_b128 v[240:243], v154 offset:3072
	v_lshl_add_u64 v[154:155], s[48:49], 0, v[136:137]
	s_mov_b32 m0, s9
	v_lshl_add_u64 v[186:187], s[48:49], 0, v[140:141]
	global_load_lds_dwordx4 v[154:155], off
	s_add_i32 m0, s9, 0x2000
	s_nop 0
	global_load_lds_dwordx4 v[186:187], off
	s_barrier
	s_waitcnt lgkmcnt(0)
	s_waitcnt lgkmcnt(0)
	v_mfma_f32_16x16x32_bf16 v[122:125], v[216:219], v[170:173], v[122:125]
	v_mfma_f32_16x16x32_bf16 v[118:121], v[236:239], v[170:173], v[118:121]
	v_mfma_f32_16x16x32_bf16 v[106:109], v[216:219], v[178:181], v[106:109]
	v_mfma_f32_16x16x32_bf16 v[102:105], v[236:239], v[178:181], v[102:105]
	v_mfma_f32_16x16x32_bf16 v[90:93], v[216:219], v[200:203], v[90:93]
	v_mfma_f32_16x16x32_bf16 v[86:89], v[236:239], v[200:203], v[86:89]
	v_mfma_f32_16x16x32_bf16 v[74:77], v[216:219], v[208:211], v[74:77]
	v_mfma_f32_16x16x32_bf16 v[70:73], v[236:239], v[208:211], v[70:73]
	v_mfma_f32_16x16x32_bf16 v[122:125], v[220:223], v[174:177], v[122:125]
	v_mfma_f32_16x16x32_bf16 v[118:121], v[240:243], v[174:177], v[118:121]
	v_mfma_f32_16x16x32_bf16 v[106:109], v[220:223], v[196:199], v[106:109]
	v_mfma_f32_16x16x32_bf16 v[102:105], v[240:243], v[196:199], v[102:105]
	v_mfma_f32_16x16x32_bf16 v[90:93], v[220:223], v[204:207], v[90:93]
	v_mfma_f32_16x16x32_bf16 v[86:89], v[240:243], v[204:207], v[86:89]
	v_mfma_f32_16x16x32_bf16 v[74:77], v[220:223], v[212:215], v[74:77]
	v_mfma_f32_16x16x32_bf16 v[70:73], v[240:243], v[212:215], v[70:73]
	s_mov_b32 m0, s57
	v_lshl_add_u64 v[188:189], s[50:51], 0, v[134:135]
	s_barrier
	ds_read_b128 v[170:173], v157 offset:16384
	ds_read_b128 v[174:177], v157 offset:17408
	ds_read_b128 v[178:181], v157 offset:18432
	ds_read_b128 v[196:199], v157 offset:19456
	ds_read_b128 v[200:203], v157 offset:20480
	ds_read_b128 v[204:207], v157 offset:21504
	ds_read_b128 v[208:211], v157 offset:22528
	ds_read_b128 v[212:215], v157 offset:23552
	global_load_lds_dwordx4 v[188:189], off
	v_lshl_add_u64 v[244:245], s[50:51], 0, v[138:139]
	s_mov_b32 m0, s58
	s_nop 0
	global_load_lds_dwordx4 v[244:245], off
	s_barrier
	s_waitcnt lgkmcnt(0)
	s_waitcnt lgkmcnt(0)
	v_mfma_f32_16x16x32_bf16 v[66:69], v[150:153], v[170:173], v[66:69]
	v_mfma_f32_16x16x32_bf16 v[62:65], v[162:165], v[170:173], v[62:65]
	v_mfma_f32_16x16x32_bf16 v[50:53], v[150:153], v[178:181], v[50:53]
	v_mfma_f32_16x16x32_bf16 v[46:49], v[162:165], v[178:181], v[46:49]
	v_mfma_f32_16x16x32_bf16 v[34:37], v[150:153], v[200:203], v[34:37]
	v_mfma_f32_16x16x32_bf16 v[30:33], v[162:165], v[200:203], v[30:33]
	v_mfma_f32_16x16x32_bf16 v[18:21], v[150:153], v[208:211], v[18:21]
	v_mfma_f32_16x16x32_bf16 v[8:11], v[162:165], v[208:211], v[8:11]
	v_mfma_f32_16x16x32_bf16 v[66:69], v[158:161], v[174:177], v[66:69]
	v_mfma_f32_16x16x32_bf16 v[62:65], v[166:169], v[174:177], v[62:65]
	v_mfma_f32_16x16x32_bf16 v[50:53], v[158:161], v[196:199], v[50:53]
	v_mfma_f32_16x16x32_bf16 v[46:49], v[166:169], v[196:199], v[46:49]
	v_mfma_f32_16x16x32_bf16 v[34:37], v[158:161], v[204:207], v[34:37]
	v_mfma_f32_16x16x32_bf16 v[30:33], v[166:169], v[204:207], v[30:33]
	v_mfma_f32_16x16x32_bf16 v[18:21], v[158:161], v[212:215], v[18:21]
	v_mfma_f32_16x16x32_bf16 v[8:11], v[166:169], v[212:215], v[8:11]
	s_barrier
; #define PG8_STAGE(bufoff, gbase, voff) do { _Pragma("unroll") for (int _i = 0; _i < 2; ++_i) \
;         __builtin_amdgcn_global_load_lds((const unsigned*)((const char*)(gbase) + (voff)[_i]), (LAS unsigned*)(lds + (bufoff) + ldsw + _i * 8192), 16, 0, 0); } while (0)
; #define PG8_LDA(dst, b, h) do { _Pragma("unroll") for (int m = 0; m < 4; ++m) _Pragma("unroll") for (int k = 0; k < 2; ++k) dst[m][k] = *(const LAS bf16x8*)(lds + PG8_SA(b, h) + aoff + m * 2048 + k * 1024); } while (0)
; #define PG8_LDB(dst, b, h) do { _Pragma("unroll") for (int n = 0; n < 2; ++n) _Pragma("unroll") for (int k = 0; k < 2; ++k) dst[n][k] = *(const LAS bf16x8*)(lds + PG8_SB(b, h) + boff + n * 2048 + k * 1024); } while (0)
; #define PG8_MMA(ai, bj, At, Bt) do { __builtin_amdgcn_s_setprio(1); _Pragma("unroll") for (int m = 0; m < 4; ++m) _Pragma("unroll") for (int n = 0; n < 2; ++n) _Pragma("unroll") for (int k = 0; k < 2; ++k) \
;         acc[ai][bj][m][n] = __builtin_amdgcn_mfma_f32_16x16x32_bf16(Bt[n][k], At[m][k], acc[ai][bj][m][n], 0, 0, 0); __builtin_amdgcn_s_setprio(0); } while (0)
; #define PG8_WAIT_V(n) asm volatile("s_waitcnt vmcnt(" #n ")" ::: "memory")
; #define PG8_WAIT_L(n) asm volatile("s_waitcnt lgkmcnt(" #n ")" ::: "memory")
; #define PG8_BAR __builtin_amdgcn_s_barrier()
; #define PG8_SCHED __builtin_amdgcn_sched_barrier(0)
; template <class Epi, class Sched>
; __device__ __forceinline__ void gemm_phase(const int TID, LAS unsigned char* lds, const int lda, const int ldb, const Sched& S, const Epi& E) {
;     ...
;             PG8_WAIT_V(6); PG8_BAR; PG8_MMA(1, 1, At, B1); PG8_BAR;
;             PG8_LDB(B0, 1, 0); PG8_SCHED; PG8_LDA(At, 1, 0); PG8_STAGE(PG8_SA(0, 1), a2 + hA, voffA);
;             PG8_WAIT_L(8); PG8_BAR; PG8_WAIT_L(0); PG8_MMA(0, 0, At, B0); PG8_BAR; PG8_SCHED;
;             PG8_LDB(B1, 1, 1); PG8_STAGE(PG8_SB(1, 0), b3, voffB);
;             PG8_BAR; PG8_WAIT_L(0); PG8_MMA(0, 1, At, B1); PG8_BAR;
;             PG8_LDA(At, 1, 1); PG8_STAGE(PG8_SA(1, 0), a3, voffA);
;             PG8_BAR; PG8_WAIT_L(0); PG8_MMA(1, 0, At, B0); PG8_BAR; PG8_SCHED;
	s_add_u32 s66, s48, 0x80000
	s_addc_u32 s67, s49, 0
	s_add_i32 s8, s8, s56
	v_lshl_add_u64 v[150:151], s[66:67], 0, v[136:137]
	s_mov_b32 m0, s8
	s_nop 0
	global_load_lds_dwordx4 v[150:151], off
	v_lshl_add_u64 v[150:151], s[66:67], 0, v[140:141]
	s_add_i32 m0, s8, 0x2000
	s_nop 0
	global_load_lds_dwordx4 v[150:151], off
	s_waitcnt vmcnt(6)
	s_barrier
	v_add_u32_e32 v166, 0x18000, v13
	v_mfma_f32_16x16x32_bf16 v[58:61], v[216:219], v[170:173], v[58:61]
	v_mfma_f32_16x16x32_bf16 v[54:57], v[236:239], v[170:173], v[54:57]
	v_mfma_f32_16x16x32_bf16 v[42:45], v[216:219], v[178:181], v[42:45]
	v_mfma_f32_16x16x32_bf16 v[38:41], v[236:239], v[178:181], v[38:41]
	ds_read_b128 v[150:153], v166
	v_mfma_f32_16x16x32_bf16 v[26:29], v[216:219], v[200:203], v[26:29]
	v_mfma_f32_16x16x32_bf16 v[22:25], v[236:239], v[200:203], v[22:25]
	ds_read_b128 v[158:161], v166 offset:1024
	v_mfma_f32_16x16x32_bf16 v[4:7], v[216:219], v[208:211], v[4:7]
	v_mfma_f32_16x16x32_bf16 v[0:3], v[236:239], v[208:211], v[0:3]
	ds_read_b128 v[162:165], v166 offset:2048
	v_mfma_f32_16x16x32_bf16 v[58:61], v[220:223], v[174:177], v[58:61]
	v_mfma_f32_16x16x32_bf16 v[54:57], v[240:243], v[174:177], v[54:57]
	ds_read_b128 v[166:169], v166 offset:3072
	v_mfma_f32_16x16x32_bf16 v[42:45], v[220:223], v[196:199], v[42:45]
	v_mfma_f32_16x16x32_bf16 v[38:41], v[240:243], v[196:199], v[38:41]
	v_mfma_f32_16x16x32_bf16 v[26:29], v[220:223], v[204:207], v[26:29]
	v_mfma_f32_16x16x32_bf16 v[22:25], v[240:243], v[204:207], v[22:25]
	v_mfma_f32_16x16x32_bf16 v[4:7], v[220:223], v[212:215], v[4:7]
	v_mfma_f32_16x16x32_bf16 v[0:3], v[240:243], v[212:215], v[0:3]
	s_add_i32 s8, 0, 0x18000
	s_barrier
	s_add_u32 s50, s50, 0x80000
	s_addc_u32 s51, s51, 0
	s_mov_b32 m0, s59
	v_lshl_add_u64 v[216:217], s[50:51], 0, v[134:135]
	ds_read_b128 v[170:173], v157 offset:32768
	ds_read_b128 v[174:177], v157 offset:33792
	ds_read_b128 v[178:181], v157 offset:34816
	ds_read_b128 v[196:199], v157 offset:35840
	ds_read_b128 v[200:203], v157 offset:36864
	ds_read_b128 v[204:207], v157 offset:37888
	ds_read_b128 v[208:211], v157 offset:38912
	ds_read_b128 v[212:215], v157 offset:39936
	global_load_lds_dwordx4 v[216:217], off
	v_lshl_add_u64 v[216:217], s[50:51], 0, v[138:139]
	s_mov_b32 m0, s60
	s_nop 0
	global_load_lds_dwordx4 v[216:217], off
	s_waitcnt lgkmcnt(8)
	s_barrier
	s_waitcnt lgkmcnt(0)
	s_waitcnt lgkmcnt(0)
	v_mfma_f32_16x16x32_bf16 v[130:133], v[150:153], v[170:173], v[130:133]
	v_mfma_f32_16x16x32_bf16 v[126:129], v[162:165], v[170:173], v[126:129]
	v_mfma_f32_16x16x32_bf16 v[114:117], v[150:153], v[178:181], v[114:117]
	v_mfma_f32_16x16x32_bf16 v[110:113], v[162:165], v[178:181], v[110:113]
	v_mfma_f32_16x16x32_bf16 v[98:101], v[150:153], v[200:203], v[98:101]
	v_mfma_f32_16x16x32_bf16 v[94:97], v[162:165], v[200:203], v[94:97]
	v_mfma_f32_16x16x32_bf16 v[82:85], v[150:153], v[208:211], v[82:85]
	v_mfma_f32_16x16x32_bf16 v[78:81], v[162:165], v[208:211], v[78:81]
	v_mfma_f32_16x16x32_bf16 v[130:133], v[158:161], v[174:177], v[130:133]
	v_mfma_f32_16x16x32_bf16 v[126:129], v[166:169], v[174:177], v[126:129]
	v_mfma_f32_16x16x32_bf16 v[114:117], v[158:161], v[196:199], v[114:117]
	v_mfma_f32_16x16x32_bf16 v[110:113], v[166:169], v[196:199], v[110:113]
	v_mfma_f32_16x16x32_bf16 v[98:101], v[158:161], v[204:207], v[98:101]
	v_mfma_f32_16x16x32_bf16 v[94:97], v[166:169], v[204:207], v[94:97]
	v_mfma_f32_16x16x32_bf16 v[82:85], v[158:161], v[212:215], v[82:85]
	v_mfma_f32_16x16x32_bf16 v[78:81], v[166:169], v[212:215], v[78:81]
	s_barrier
	s_add_i32 s9, 0, 0x1c000
	s_add_i32 s8, s8, s56
	v_add_u32_e32 v182, s9, v13
	v_lshl_add_u64 v[154:155], v[154:155], 0, s[36:37]
	s_mov_b32 m0, s8
	ds_read_b128 v[216:219], v182
	ds_read_b128 v[220:223], v182 offset:1024
	ds_read_b128 v[236:239], v182 offset:2048
	ds_read_b128 v[240:243], v182 offset:3072
	global_load_lds_dwordx4 v[154:155], off
	v_lshl_add_u64 v[154:155], v[186:187], 0, s[36:37]
	s_add_i32 m0, s8, 0x2000
	s_nop 0
	global_load_lds_dwordx4 v[154:155], off
	s_barrier
	s_waitcnt lgkmcnt(0)
	s_waitcnt lgkmcnt(0)
	v_mfma_f32_16x16x32_bf16 v[122:125], v[216:219], v[170:173], v[122:125]
	v_mfma_f32_16x16x32_bf16 v[118:121], v[236:239], v[170:173], v[118:121]
	v_mfma_f32_16x16x32_bf16 v[106:109], v[216:219], v[178:181], v[106:109]
	v_mfma_f32_16x16x32_bf16 v[102:105], v[236:239], v[178:181], v[102:105]
	v_mfma_f32_16x16x32_bf16 v[90:93], v[216:219], v[200:203], v[90:93]
	v_mfma_f32_16x16x32_bf16 v[86:89], v[236:239], v[200:203], v[86:89]
	v_mfma_f32_16x16x32_bf16 v[74:77], v[216:219], v[208:211], v[74:77]
	v_mfma_f32_16x16x32_bf16 v[70:73], v[236:239], v[208:211], v[70:73]
	v_mfma_f32_16x16x32_bf16 v[122:125], v[220:223], v[174:177], v[122:125]
	v_mfma_f32_16x16x32_bf16 v[118:121], v[240:243], v[174:177], v[118:121]
	v_mfma_f32_16x16x32_bf16 v[106:109], v[220:223], v[196:199], v[106:109]
	v_mfma_f32_16x16x32_bf16 v[102:105], v[240:243], v[196:199], v[102:105]
	v_mfma_f32_16x16x32_bf16 v[90:93], v[220:223], v[204:207], v[90:93]
	v_mfma_f32_16x16x32_bf16 v[86:89], v[240:243], v[204:207], v[86:89]
	v_mfma_f32_16x16x32_bf16 v[74:77], v[220:223], v[212:215], v[74:77]
	v_mfma_f32_16x16x32_bf16 v[70:73], v[240:243], v[212:215], v[70:73]
	s_mov_b32 m0, s62
	v_lshl_add_u64 v[154:155], v[188:189], 0, s[36:37]
	s_barrier
; #define PG8_STAGE(bufoff, gbase, voff) do { _Pragma("unroll") for (int _i = 0; _i < 2; ++_i) \
;         __builtin_amdgcn_global_load_lds((const unsigned*)((const char*)(gbase) + (voff)[_i]), (LAS unsigned*)(lds + (bufoff) + ldsw + _i * 8192), 16, 0, 0); } while (0)
; #define PG8_MMA(ai, bj, At, Bt) do { __builtin_amdgcn_s_setprio(1); _Pragma("unroll") for (int m = 0; m < 4; ++m) _Pragma("unroll") for (int n = 0; n < 2; ++n) _Pragma("unroll") for (int k = 0; k < 2; ++k) \
;         acc[ai][bj][m][n] = __builtin_amdgcn_mfma_f32_16x16x32_bf16(Bt[n][k], At[m][k], acc[ai][bj][m][n], 0, 0, 0); __builtin_amdgcn_s_setprio(0); } while (0)
; #define PG8_WAIT_V(n) asm volatile("s_waitcnt vmcnt(" #n ")" ::: "memory")
; #define PG8_WAIT_L(n) asm volatile("s_waitcnt lgkmcnt(" #n ")" ::: "memory")
; #define PG8_BAR __builtin_amdgcn_s_barrier()
; #define PG8_SCHED __builtin_amdgcn_sched_barrier(0)
; template <class Epi, class Sched>
; __device__ __forceinline__ void gemm_phase(const int TID, LAS unsigned char* lds, const int lda, const int ldb, const Sched& S, const Epi& E) {
;     ...
;             PG8_BAR; PG8_WAIT_L(0); PG8_MMA(1, 0, At, B0); PG8_BAR; PG8_SCHED;
;             PG8_STAGE(PG8_SB(1, 1), b3 + hB, voffB);
;             PG8_WAIT_V(6); PG8_BAR; PG8_MMA(1, 1, At, B1); PG8_BAR;
	ds_read_b128 v[170:173], v157 offset:49152
	ds_read_b128 v[174:177], v157 offset:50176
	ds_read_b128 v[178:181], v157 offset:51200
	ds_read_b128 v[196:199], v157 offset:52224
	ds_read_b128 v[200:203], v157 offset:53248
	ds_read_b128 v[204:207], v157 offset:54272
	ds_read_b128 v[208:211], v157 offset:55296
	ds_read_b128 v[212:215], v157 offset:56320
	global_load_lds_dwordx4 v[154:155], off
	v_lshl_add_u64 v[154:155], v[244:245], 0, s[36:37]
	s_mov_b32 m0, s63
	s_nop 0
	global_load_lds_dwordx4 v[154:155], off
	s_barrier
	s_waitcnt lgkmcnt(0)
	s_waitcnt lgkmcnt(0)
	v_mfma_f32_16x16x32_bf16 v[66:69], v[150:153], v[170:173], v[66:69]
	v_mfma_f32_16x16x32_bf16 v[62:65], v[162:165], v[170:173], v[62:65]
	v_mfma_f32_16x16x32_bf16 v[50:53], v[150:153], v[178:181], v[50:53]
	v_mfma_f32_16x16x32_bf16 v[46:49], v[162:165], v[178:181], v[46:49]
	v_mfma_f32_16x16x32_bf16 v[34:37], v[150:153], v[200:203], v[34:37]
	v_mfma_f32_16x16x32_bf16 v[30:33], v[162:165], v[200:203], v[30:33]
	v_mfma_f32_16x16x32_bf16 v[18:21], v[150:153], v[208:211], v[18:21]
	v_mfma_f32_16x16x32_bf16 v[8:11], v[162:165], v[208:211], v[8:11]
	v_mfma_f32_16x16x32_bf16 v[66:69], v[158:161], v[174:177], v[66:69]
	v_mfma_f32_16x16x32_bf16 v[62:65], v[166:169], v[174:177], v[62:65]
	v_mfma_f32_16x16x32_bf16 v[50:53], v[158:161], v[196:199], v[50:53]
	v_mfma_f32_16x16x32_bf16 v[46:49], v[166:169], v[196:199], v[46:49]
	v_mfma_f32_16x16x32_bf16 v[34:37], v[158:161], v[204:207], v[34:37]
	v_mfma_f32_16x16x32_bf16 v[30:33], v[166:169], v[204:207], v[30:33]
	v_mfma_f32_16x16x32_bf16 v[18:21], v[158:161], v[212:215], v[18:21]
	v_mfma_f32_16x16x32_bf16 v[8:11], v[166:169], v[212:215], v[8:11]
	s_barrier
	s_add_u32 s48, s48, 0x80080
	s_addc_u32 s49, s49, 0
	s_add_i32 s8, s9, s56
	v_lshl_add_u64 v[150:151], s[48:49], 0, v[136:137]
	s_mov_b32 m0, s8
	s_nop 0
	global_load_lds_dwordx4 v[150:151], off
	v_lshl_add_u64 v[150:151], s[48:49], 0, v[140:141]
	s_add_i32 m0, s8, 0x2000
	s_nop 0
	global_load_lds_dwordx4 v[150:151], off
	s_waitcnt vmcnt(6)
	s_barrier
	v_add_u32_e32 v154, 0x10000, v13
	v_mfma_f32_16x16x32_bf16 v[58:61], v[216:219], v[170:173], v[58:61]
	v_mfma_f32_16x16x32_bf16 v[54:57], v[236:239], v[170:173], v[54:57]
	v_mfma_f32_16x16x32_bf16 v[42:45], v[216:219], v[178:181], v[42:45]
	v_mfma_f32_16x16x32_bf16 v[38:41], v[236:239], v[178:181], v[38:41]
	ds_read_b128 v[150:153], v154
	v_mfma_f32_16x16x32_bf16 v[26:29], v[216:219], v[200:203], v[26:29]
	v_mfma_f32_16x16x32_bf16 v[22:25], v[236:239], v[200:203], v[22:25]
	ds_read_b128 v[158:161], v154 offset:1024
	v_mfma_f32_16x16x32_bf16 v[4:7], v[216:219], v[208:211], v[4:7]
	v_mfma_f32_16x16x32_bf16 v[0:3], v[236:239], v[208:211], v[0:3]
	ds_read_b128 v[162:165], v154 offset:2048
	v_mfma_f32_16x16x32_bf16 v[58:61], v[220:223], v[174:177], v[58:61]
	v_mfma_f32_16x16x32_bf16 v[54:57], v[240:243], v[174:177], v[54:57]
	ds_read_b128 v[166:169], v154 offset:3072
	v_mfma_f32_16x16x32_bf16 v[42:45], v[220:223], v[196:199], v[42:45]
	v_mfma_f32_16x16x32_bf16 v[38:41], v[240:243], v[196:199], v[38:41]
	v_mfma_f32_16x16x32_bf16 v[26:29], v[220:223], v[204:207], v[26:29]
	v_mfma_f32_16x16x32_bf16 v[22:25], v[240:243], v[204:207], v[22:25]
	v_mfma_f32_16x16x32_bf16 v[4:7], v[220:223], v[212:215], v[4:7]
	v_mfma_f32_16x16x32_bf16 v[0:3], v[240:243], v[212:215], v[0:3]
	s_add_i32 s29, s29, 2
	s_add_u32 s3, s3, 0x100
	s_addc_u32 s24, s24, 0
	s_add_u32 s46, s46, 0x100
	s_addc_u32 s47, s47, 0
	s_add_u32 s8, s46, 0xfff80080
	s_addc_u32 s9, s47, -1
	s_add_i32 s10, 0, 0x10000
	s_cmp_eq_u32 s29, 28
	s_cselect_b32 s51, s43, s9
	s_cselect_b32 s50, s42, s8
	s_cselect_b32 s49, s45, s24
	s_cselect_b32 s48, s44, s3
	v_lshl_add_u64 v[154:155], s[46:47], 0, v[148:149]
	s_add_i32 m0, s57, 0xc000
	s_cmp_gt_u32 s29, 29
	s_barrier
	s_cbranch_scc0 .Lk1_body
	s_setprio 0
	s_waitcnt lgkmcnt(0)
	s_lshl_b32 s3, s40, 8
	s_sub_i32 s8, s65, 18
	s_add_i32 s3, s3, s61
	s_lshl_b32 s24, s65, 8
	s_cmp_gt_u32 s8, 23
	v_or_b32_e32 v158, s3, v12
	s_mov_b64 s[40:41], -1
	s_cbranch_scc0 .LBB0_1295
	s_cmp_gt_i32 s65, 1
	s_cselect_b64 s[46:47], -1, 0
	v_mad_i64_i32 v[150:151], s[40:41], v158, s4, 0
	v_or_b32_e32 v182, s24, v156
	s_mov_b64 s[40:41], -1
	s_and_b64 vcc, exec, s[46:47]
	v_lshl_add_u64 v[150:151], s[0:1], 0, v[150:151]
	s_cbranch_vccz .LBB0_1232
	v_lshl_add_u64 v[152:153], v[182:183], 1, v[150:151]
	s_mov_b64 s[40:41], 0
